# SwiGLU epilogues: rstd^2 folded into the sigmoid reciprocal (rcp(k+k*e), k = ssq/1024+eps), 40 fewer VALU per epilogue
# speedup vs baseline: 1.0036x; 1.0016x over previous
.LBB0_173:
	v_mov_b32_e32 v254, 1.0
	v_lshl_add_u32 v202, s20, 8, v1
	s_and_b32 s71, s55, 1
	s_lshl_b32 s71, s71, 12
	s_add_i32 s71, s71, 0x20000
	v_lshl_add_u32 v206, v1, 4, s71
	v_add_u32_e32 v156, 0x80, v202
	ds_read_b128 v[170:173], v206
	ds_read_b128 v[174:177], v206 offset:256
	ds_read_b128 v[178:181], v206 offset:512
	ds_read_b128 v[182:185], v206 offset:768
	ds_read_b128 v[186:189], v206 offset:2048
	ds_read_b128 v[190:193], v206 offset:2304
	ds_read_b128 v[194:197], v206 offset:2560
	ds_read_b128 v[198:201], v206 offset:2816
	v_pk_mul_f32 v[124:125], v[128:129], v[124:125]
	v_pk_mul_f32 v[122:123], v[126:127], v[122:123]
	v_pk_mul_f32 v[116:117], v[120:121], v[116:117]
	v_lshl_or_b32 v204, s68, 7, v164
	v_pk_mul_f32 v[114:115], v[118:119], v[114:115]
	v_mul_u32_u24_e32 v207, s67, v202
	v_lshl_add_u32 v207, v204, 1, v207
	v_pk_mul_f32 v[108:109], v[112:113], v[108:109]
	v_pk_mul_f32 v[106:107], v[110:111], v[106:107]
	v_pk_mul_f32 v[100:101], v[104:105], v[100:101]
	v_pk_mul_f32 v[98:99], v[102:103], v[98:99]
	v_pk_mul_f32 v[92:93], v[96:97], v[92:93]
	v_pk_mul_f32 v[90:91], v[94:95], v[90:91]
	v_pk_mul_f32 v[84:85], v[88:89], v[84:85]
	v_pk_mul_f32 v[82:83], v[86:87], v[82:83]
	v_pk_mul_f32 v[76:77], v[80:81], v[76:77]
	v_pk_mul_f32 v[74:75], v[78:79], v[74:75]
	v_pk_mul_f32 v[68:69], v[72:73], v[68:69]
	v_pk_mul_f32 v[66:67], v[70:71], v[66:67]
	v_pk_mul_f32 v[60:61], v[64:65], v[60:61]
	v_pk_mul_f32 v[58:59], v[62:63], v[58:59]
	v_pk_mul_f32 v[52:53], v[56:57], v[52:53]
	v_pk_mul_f32 v[50:51], v[54:55], v[50:51]
	v_pk_mul_f32 v[44:45], v[48:49], v[44:45]
	v_pk_mul_f32 v[42:43], v[46:47], v[42:43]
	v_pk_mul_f32 v[36:37], v[40:41], v[36:37]
	v_pk_mul_f32 v[34:35], v[38:39], v[34:35]
	v_pk_mul_f32 v[28:29], v[32:33], v[28:29]
	v_pk_mul_f32 v[26:27], v[30:31], v[26:27]
	v_pk_mul_f32 v[20:21], v[24:25], v[20:21]
	v_pk_mul_f32 v[18:19], v[22:23], v[18:19]
	v_pk_mul_f32 v[12:13], v[16:17], v[12:13]
	v_pk_mul_f32 v[10:11], v[14:15], v[10:11]
	v_pk_mul_f32 v[4:5], v[8:9], v[4:5]
	v_pk_mul_f32 v[2:3], v[6:7], v[2:3]
	s_andn2_b64 vcc, exec, s[2:3]
	s_mov_b64 s[2:3], -1
	v_readlane_b32 s70, v253, 14
	v_readlane_b32 s71, v253, 15
	s_waitcnt lgkmcnt(0)
	v_add_f32_e32 v152, v170, v171
	v_add_f32_e32 v153, v172, v173
	v_add_f32_e32 v149, v152, v153
	v_fmamk_f32 v208, v149, 0x3a800000, v168
	v_add_f32_e32 v174, v174, v175
	v_add_f32_e32 v176, v176, v177
	v_rsq_f32_e32 v163, v208
	v_add_f32_e32 v151, v174, v176
	v_add_f32_e32 v178, v178, v179
	v_add_f32_e32 v180, v180, v181
	v_add_f32_e32 v152, v178, v180
	v_add_f32_e32 v182, v182, v183
	v_add_f32_e32 v184, v184, v185
	v_add_f32_e32 v153, v182, v184
	v_add_f32_e32 v186, v186, v187
	v_add_f32_e32 v188, v188, v189
	v_add_f32_e32 v155, v186, v188
	v_add_f32_e32 v190, v190, v191
	v_add_f32_e32 v192, v192, v193
	v_add_f32_e32 v157, v190, v192
	v_add_f32_e32 v194, v194, v195
	v_add_f32_e32 v196, v196, v197
	v_add_f32_e32 v159, v194, v196
	v_add_f32_e32 v198, v198, v199
	v_add_f32_e32 v200, v200, v201
	v_add_f32_e32 v161, v198, v200
	v_fmamk_f32 v209, v151, 0x3a800000, v168
	v_fmamk_f32 v210, v152, 0x3a800000, v168
	v_fmamk_f32 v211, v153, 0x3a800000, v168
	v_fmamk_f32 v212, v155, 0x3a800000, v168
	v_fmamk_f32 v213, v157, 0x3a800000, v168
	v_fmamk_f32 v214, v159, 0x3a800000, v168
	v_fmamk_f32 v215, v161, 0x3a800000, v168
	v_rsq_f32_e32 v169, v210
	v_rsq_f32_e32 v151, v214
	v_mul_f32_e32 v157, 0xbfb8aa3b, v163
	v_rsq_f32_e32 v161, v209
	v_rsq_f32_e32 v149, v215
	v_pk_mul_f32 v[174:175], v[126:127], v[156:157] op_sel:[0,1] op_sel_hi:[1,1]
	v_exp_f32_e32 v174, v174
	v_exp_f32_e32 v175, v175
	s_nop 0
	v_pk_fma_f32 v[174:175], v[174:175], v[208:209], v[208:209] op_sel:[0,0,0] op_sel_hi:[1,0,0]
	v_rcp_f32_e32 v174, v174
	v_rcp_f32_e32 v175, v175
	v_pk_mul_f32 v[128:129], v[128:129], v[156:157] op_sel:[0,1] op_sel_hi:[1,1]
	v_exp_f32_e32 v128, v128
	v_exp_f32_e32 v129, v129
	v_rsq_f32_e32 v173, v211
	v_rsq_f32_e32 v176, v212
	v_pk_fma_f32 v[128:129], v[128:129], v[208:209], v[208:209] op_sel:[0,0,0] op_sel_hi:[1,0,0]
	v_rcp_f32_e32 v128, v128
	v_rcp_f32_e32 v129, v129
	v_pk_mul_f32 v[122:123], v[122:123], v[174:175]
	v_pk_mul_f32 v[124:125], v[124:125], v[128:129]
	v_pk_mul_f32 v[128:129], v[118:119], v[156:157] op_sel:[0,1] op_sel_hi:[1,1]
	v_exp_f32_e32 v128, v128
	v_exp_f32_e32 v129, v129
	s_nop 0
	v_pk_fma_f32 v[126:127], v[128:129], v[208:209], v[208:209] op_sel:[0,0,0] op_sel_hi:[1,0,0]
	v_mul_f32_e32 v128, v120, v157
	v_mul_f32_e32 v129, v121, v157
	v_exp_f32_e32 v128, v128
	v_exp_f32_e32 v129, v129
	v_rcp_f32_e32 v126, v126
	v_rcp_f32_e32 v127, v127
	v_fma_f32 v120, v128, v208, v208
	v_fma_f32 v121, v129, v208, v208
	v_rcp_f32_e32 v120, v120
	v_rcp_f32_e32 v121, v121
	v_pk_mul_f32 v[118:119], v[114:115], v[126:127]
	v_rsq_f32_e32 v155, v213
	v_pk_mul_f32 v[120:121], v[116:117], v[120:121]
	v_cvt_pk_bf16_f32 v116, v122, v123
	v_cvt_pk_bf16_f32 v117, v124, v125
	v_cvt_pk_bf16_f32 v118, v118, v119
	v_cvt_pk_bf16_f32 v119, v120, v121
	global_store_dwordx4 v207, v[116:119], s[4:5]
	s_nop 1
	v_mul_f32_e32 v119, 0xbfb8aa3b, v161
	v_pk_mul_f32 v[120:121], v[110:111], v[118:119] op_sel:[0,1] op_sel_hi:[1,1]
	v_exp_f32_e32 v120, v120
	v_exp_f32_e32 v121, v121
	v_pk_mul_f32 v[122:123], v[112:113], v[118:119] op_sel:[0,1] op_sel_hi:[1,1]
	v_exp_f32_e32 v122, v122
	v_exp_f32_e32 v123, v123
	v_pk_fma_f32 v[120:121], v[120:121], v[208:209], v[208:209] op_sel:[0,1,1] op_sel_hi:[1,1,1]
	v_rcp_f32_e32 v120, v120
	v_rcp_f32_e32 v121, v121
	v_pk_fma_f32 v[122:123], v[122:123], v[208:209], v[208:209] op_sel:[0,1,1] op_sel_hi:[1,1,1]
	v_rcp_f32_e32 v112, v122
	v_rcp_f32_e32 v113, v123
	v_pk_mul_f32 v[106:107], v[106:107], v[120:121]
	v_pk_mul_f32 v[108:109], v[108:109], v[112:113]
	v_pk_mul_f32 v[112:113], v[102:103], v[118:119] op_sel:[0,1] op_sel_hi:[1,1]
	v_exp_f32_e32 v112, v112
	v_exp_f32_e32 v113, v113
	s_nop 0
	v_pk_fma_f32 v[110:111], v[112:113], v[208:209], v[208:209] op_sel:[0,1,1] op_sel_hi:[1,1,1]
	v_pk_mul_f32 v[112:113], v[104:105], v[118:119] op_sel:[0,1] op_sel_hi:[1,1]
	v_exp_f32_e32 v112, v112
	v_exp_f32_e32 v113, v113
	v_rcp_f32_e32 v110, v110
	v_rcp_f32_e32 v111, v111
	v_pk_fma_f32 v[112:113], v[112:113], v[208:209], v[208:209] op_sel:[0,1,1] op_sel_hi:[1,1,1]
	v_rcp_f32_e32 v104, v112
	v_rcp_f32_e32 v105, v113
	v_pk_mul_f32 v[102:103], v[98:99], v[110:111]
	v_pk_mul_f32 v[104:105], v[100:101], v[104:105]
	v_cvt_pk_bf16_f32 v98, v106, v107
	v_cvt_pk_bf16_f32 v99, v108, v109
	v_cvt_pk_bf16_f32 v100, v102, v103
	v_cvt_pk_bf16_f32 v101, v104, v105
	s_add_u32 s28, s4, 0x16000
	s_addc_u32 s29, s5, 0
	global_store_dwordx4 v207, v[98:101], s[28:29]
	s_nop 1
	v_mul_f32_e32 v101, 0xbfb8aa3b, v169
	v_pk_mul_f32 v[102:103], v[94:95], v[100:101] op_sel:[0,1] op_sel_hi:[1,1]
	v_exp_f32_e32 v102, v102
	v_exp_f32_e32 v103, v103
	v_pk_mul_f32 v[104:105], v[96:97], v[100:101] op_sel:[0,1] op_sel_hi:[1,1]
	v_exp_f32_e32 v104, v104
	v_exp_f32_e32 v105, v105
	v_pk_fma_f32 v[102:103], v[102:103], v[210:211], v[210:211] op_sel:[0,0,0] op_sel_hi:[1,0,0]
	v_rcp_f32_e32 v102, v102
	v_rcp_f32_e32 v103, v103
	v_pk_fma_f32 v[104:105], v[104:105], v[210:211], v[210:211] op_sel:[0,0,0] op_sel_hi:[1,0,0]
	v_rcp_f32_e32 v96, v104
	v_rcp_f32_e32 v97, v105
	v_pk_mul_f32 v[90:91], v[90:91], v[102:103]
	v_pk_mul_f32 v[92:93], v[92:93], v[96:97]
	v_pk_mul_f32 v[96:97], v[86:87], v[100:101] op_sel:[0,1] op_sel_hi:[1,1]
	v_exp_f32_e32 v96, v96
	v_exp_f32_e32 v97, v97
	s_nop 0
	v_pk_fma_f32 v[94:95], v[96:97], v[210:211], v[210:211] op_sel:[0,0,0] op_sel_hi:[1,0,0]
	v_pk_mul_f32 v[96:97], v[88:89], v[100:101] op_sel:[0,1] op_sel_hi:[1,1]
	v_exp_f32_e32 v96, v96
	v_exp_f32_e32 v97, v97
	v_rcp_f32_e32 v94, v94
	v_rcp_f32_e32 v95, v95
	v_pk_fma_f32 v[96:97], v[96:97], v[210:211], v[210:211] op_sel:[0,0,0] op_sel_hi:[1,0,0]
	v_rcp_f32_e32 v88, v96
	v_rcp_f32_e32 v89, v97
	v_pk_mul_f32 v[86:87], v[82:83], v[94:95]
	v_pk_mul_f32 v[88:89], v[84:85], v[88:89]
	v_cvt_pk_bf16_f32 v82, v90, v91
	v_cvt_pk_bf16_f32 v83, v92, v93
	v_cvt_pk_bf16_f32 v84, v86, v87
	v_cvt_pk_bf16_f32 v85, v88, v89
	s_add_u32 s28, s4, 0x2c000
	s_addc_u32 s29, s5, 0
	global_store_dwordx4 v207, v[82:85], s[28:29]
	s_nop 1
	v_mul_f32_e32 v85, 0xbfb8aa3b, v173
	v_pk_mul_f32 v[86:87], v[78:79], v[84:85] op_sel:[0,1] op_sel_hi:[1,1]
	v_exp_f32_e32 v86, v86
	v_exp_f32_e32 v87, v87
	v_pk_mul_f32 v[88:89], v[80:81], v[84:85] op_sel:[0,1] op_sel_hi:[1,1]
	v_exp_f32_e32 v88, v88
	v_exp_f32_e32 v89, v89
	v_pk_fma_f32 v[86:87], v[86:87], v[210:211], v[210:211] op_sel:[0,1,1] op_sel_hi:[1,1,1]
	v_rcp_f32_e32 v86, v86
	v_rcp_f32_e32 v87, v87
	v_pk_fma_f32 v[88:89], v[88:89], v[210:211], v[210:211] op_sel:[0,1,1] op_sel_hi:[1,1,1]
	v_rcp_f32_e32 v80, v88
	v_rcp_f32_e32 v81, v89
	v_pk_mul_f32 v[74:75], v[74:75], v[86:87]
	v_pk_mul_f32 v[76:77], v[76:77], v[80:81]
	v_pk_mul_f32 v[80:81], v[70:71], v[84:85] op_sel:[0,1] op_sel_hi:[1,1]
	v_exp_f32_e32 v80, v80
	v_exp_f32_e32 v81, v81
	s_nop 0
	v_pk_fma_f32 v[78:79], v[80:81], v[210:211], v[210:211] op_sel:[0,1,1] op_sel_hi:[1,1,1]
	v_pk_mul_f32 v[80:81], v[72:73], v[84:85] op_sel:[0,1] op_sel_hi:[1,1]
	v_exp_f32_e32 v80, v80
	v_exp_f32_e32 v81, v81
	v_rcp_f32_e32 v78, v78
	v_rcp_f32_e32 v79, v79
	v_pk_fma_f32 v[80:81], v[80:81], v[210:211], v[210:211] op_sel:[0,1,1] op_sel_hi:[1,1,1]
	v_rcp_f32_e32 v72, v80
	v_rcp_f32_e32 v73, v81
	v_pk_mul_f32 v[70:71], v[66:67], v[78:79]
	v_pk_mul_f32 v[72:73], v[68:69], v[72:73]
	v_cvt_pk_bf16_f32 v66, v74, v75
	v_cvt_pk_bf16_f32 v67, v76, v77
	v_cvt_pk_bf16_f32 v68, v70, v71
	v_cvt_pk_bf16_f32 v69, v72, v73
	s_add_u32 s28, s4, 0x42000
	s_addc_u32 s29, s5, 0
	global_store_dwordx4 v207, v[66:69], s[28:29]
	s_nop 1
	v_mul_f32_e32 v69, 0xbfb8aa3b, v176
	v_pk_mul_f32 v[70:71], v[62:63], v[68:69] op_sel:[0,1] op_sel_hi:[1,1]
	v_exp_f32_e32 v70, v70
	v_exp_f32_e32 v71, v71
	v_pk_mul_f32 v[72:73], v[64:65], v[68:69] op_sel:[0,1] op_sel_hi:[1,1]
	v_exp_f32_e32 v72, v72
	v_exp_f32_e32 v73, v73
	v_pk_fma_f32 v[70:71], v[70:71], v[212:213], v[212:213] op_sel:[0,0,0] op_sel_hi:[1,0,0]
	v_rcp_f32_e32 v70, v70
	v_rcp_f32_e32 v71, v71
	v_pk_fma_f32 v[72:73], v[72:73], v[212:213], v[212:213] op_sel:[0,0,0] op_sel_hi:[1,0,0]
	v_rcp_f32_e32 v64, v72
	v_rcp_f32_e32 v65, v73
	v_pk_mul_f32 v[58:59], v[58:59], v[70:71]
	v_pk_mul_f32 v[60:61], v[60:61], v[64:65]
	v_pk_mul_f32 v[64:65], v[54:55], v[68:69] op_sel:[0,1] op_sel_hi:[1,1]
	v_exp_f32_e32 v64, v64
	v_exp_f32_e32 v65, v65
	s_nop 0
	v_pk_fma_f32 v[62:63], v[64:65], v[212:213], v[212:213] op_sel:[0,0,0] op_sel_hi:[1,0,0]
	v_pk_mul_f32 v[64:65], v[56:57], v[68:69] op_sel:[0,1] op_sel_hi:[1,1]
	v_exp_f32_e32 v64, v64
	v_exp_f32_e32 v65, v65
	v_rcp_f32_e32 v62, v62
	v_rcp_f32_e32 v63, v63
	v_pk_fma_f32 v[64:65], v[64:65], v[212:213], v[212:213] op_sel:[0,0,0] op_sel_hi:[1,0,0]
	v_rcp_f32_e32 v56, v64
	v_rcp_f32_e32 v57, v65
	v_pk_mul_f32 v[54:55], v[50:51], v[62:63]
	v_pk_mul_f32 v[56:57], v[52:53], v[56:57]
	v_cvt_pk_bf16_f32 v50, v58, v59
	v_cvt_pk_bf16_f32 v51, v60, v61
	v_cvt_pk_bf16_f32 v52, v54, v55
	v_cvt_pk_bf16_f32 v53, v56, v57
	s_add_u32 s28, s4, 0xb0000
	s_addc_u32 s29, s5, 0
	global_store_dwordx4 v207, v[50:53], s[28:29]
	s_nop 1
	v_mul_f32_e32 v53, 0xbfb8aa3b, v155
	v_pk_mul_f32 v[54:55], v[46:47], v[52:53] op_sel:[0,1] op_sel_hi:[1,1]
	v_exp_f32_e32 v54, v54
	v_exp_f32_e32 v55, v55
	v_pk_mul_f32 v[56:57], v[48:49], v[52:53] op_sel:[0,1] op_sel_hi:[1,1]
	v_exp_f32_e32 v56, v56
	v_exp_f32_e32 v57, v57
	v_pk_fma_f32 v[54:55], v[54:55], v[212:213], v[212:213] op_sel:[0,1,1] op_sel_hi:[1,1,1]
	v_rcp_f32_e32 v54, v54
	v_rcp_f32_e32 v55, v55
	v_pk_fma_f32 v[56:57], v[56:57], v[212:213], v[212:213] op_sel:[0,1,1] op_sel_hi:[1,1,1]
	v_rcp_f32_e32 v48, v56
	v_rcp_f32_e32 v49, v57
	v_pk_mul_f32 v[42:43], v[42:43], v[54:55]
	v_pk_mul_f32 v[44:45], v[44:45], v[48:49]
	v_pk_mul_f32 v[48:49], v[38:39], v[52:53] op_sel:[0,1] op_sel_hi:[1,1]
	v_exp_f32_e32 v48, v48
	v_exp_f32_e32 v49, v49
	s_nop 0
	v_pk_fma_f32 v[46:47], v[48:49], v[212:213], v[212:213] op_sel:[0,1,1] op_sel_hi:[1,1,1]
	v_pk_mul_f32 v[48:49], v[40:41], v[52:53] op_sel:[0,1] op_sel_hi:[1,1]
	v_exp_f32_e32 v48, v48
	v_exp_f32_e32 v49, v49
	v_rcp_f32_e32 v46, v46
	v_rcp_f32_e32 v47, v47
	v_pk_fma_f32 v[48:49], v[48:49], v[212:213], v[212:213] op_sel:[0,1,1] op_sel_hi:[1,1,1]
	v_rcp_f32_e32 v40, v48
	v_rcp_f32_e32 v41, v49
	v_pk_mul_f32 v[38:39], v[34:35], v[46:47]
	v_pk_mul_f32 v[40:41], v[36:37], v[40:41]
	v_cvt_pk_bf16_f32 v34, v42, v43
	v_cvt_pk_bf16_f32 v35, v44, v45
	v_cvt_pk_bf16_f32 v36, v38, v39
	v_cvt_pk_bf16_f32 v37, v40, v41
	s_add_u32 s28, s4, 0xc6000
	s_addc_u32 s29, s5, 0
	global_store_dwordx4 v207, v[34:37], s[28:29]
	s_nop 1
	v_mul_f32_e32 v37, 0xbfb8aa3b, v151
	v_pk_mul_f32 v[38:39], v[30:31], v[36:37] op_sel:[0,1] op_sel_hi:[1,1]
	v_exp_f32_e32 v38, v38
	v_exp_f32_e32 v39, v39
	v_pk_mul_f32 v[40:41], v[32:33], v[36:37] op_sel:[0,1] op_sel_hi:[1,1]
	v_exp_f32_e32 v40, v40
	v_exp_f32_e32 v41, v41
	v_pk_fma_f32 v[38:39], v[38:39], v[214:215], v[214:215] op_sel:[0,0,0] op_sel_hi:[1,0,0]
	v_rcp_f32_e32 v38, v38
	v_rcp_f32_e32 v39, v39
	v_pk_fma_f32 v[40:41], v[40:41], v[214:215], v[214:215] op_sel:[0,0,0] op_sel_hi:[1,0,0]
	v_rcp_f32_e32 v32, v40
	v_rcp_f32_e32 v33, v41
	v_pk_mul_f32 v[26:27], v[26:27], v[38:39]
	v_pk_mul_f32 v[28:29], v[28:29], v[32:33]
	v_pk_mul_f32 v[32:33], v[22:23], v[36:37] op_sel:[0,1] op_sel_hi:[1,1]
	v_exp_f32_e32 v32, v32
	v_exp_f32_e32 v33, v33
	s_nop 0
	v_pk_fma_f32 v[30:31], v[32:33], v[214:215], v[214:215] op_sel:[0,0,0] op_sel_hi:[1,0,0]
	v_pk_mul_f32 v[32:33], v[24:25], v[36:37] op_sel:[0,1] op_sel_hi:[1,1]
	v_exp_f32_e32 v32, v32
	v_exp_f32_e32 v33, v33
	v_rcp_f32_e32 v30, v30
	v_rcp_f32_e32 v31, v31
	v_pk_fma_f32 v[32:33], v[32:33], v[214:215], v[214:215] op_sel:[0,0,0] op_sel_hi:[1,0,0]
	v_rcp_f32_e32 v24, v32
	v_rcp_f32_e32 v25, v33
	v_pk_mul_f32 v[22:23], v[18:19], v[30:31]
	v_pk_mul_f32 v[24:25], v[20:21], v[24:25]
	v_cvt_pk_bf16_f32 v18, v26, v27
	v_cvt_pk_bf16_f32 v19, v28, v29
	v_cvt_pk_bf16_f32 v20, v22, v23
	v_cvt_pk_bf16_f32 v21, v24, v25
	s_add_u32 s28, s4, 0xdc000
	s_addc_u32 s29, s5, 0
	global_store_dwordx4 v207, v[18:21], s[28:29]
	s_nop 1
	v_mul_f32_e32 v21, 0xbfb8aa3b, v149
	v_pk_mul_f32 v[22:23], v[14:15], v[20:21] op_sel:[0,1] op_sel_hi:[1,1]
	v_exp_f32_e32 v22, v22
	v_exp_f32_e32 v23, v23
	v_pk_mul_f32 v[24:25], v[16:17], v[20:21] op_sel:[0,1] op_sel_hi:[1,1]
	v_exp_f32_e32 v24, v24
	v_exp_f32_e32 v25, v25
	v_pk_fma_f32 v[22:23], v[22:23], v[214:215], v[214:215] op_sel:[0,1,1] op_sel_hi:[1,1,1]
	v_rcp_f32_e32 v22, v22
	v_rcp_f32_e32 v23, v23
	v_pk_fma_f32 v[24:25], v[24:25], v[214:215], v[214:215] op_sel:[0,1,1] op_sel_hi:[1,1,1]
	v_rcp_f32_e32 v16, v24
	v_rcp_f32_e32 v17, v25
	v_pk_mul_f32 v[10:11], v[10:11], v[22:23]
	v_pk_mul_f32 v[12:13], v[12:13], v[16:17]
	v_pk_mul_f32 v[16:17], v[6:7], v[20:21] op_sel:[0,1] op_sel_hi:[1,1]
	v_exp_f32_e32 v16, v16
	v_exp_f32_e32 v17, v17
	s_nop 0
	v_pk_fma_f32 v[14:15], v[16:17], v[214:215], v[214:215] op_sel:[0,1,1] op_sel_hi:[1,1,1]
	v_pk_mul_f32 v[16:17], v[8:9], v[20:21] op_sel:[0,1] op_sel_hi:[1,1]
	v_exp_f32_e32 v16, v16
	v_exp_f32_e32 v17, v17
	v_rcp_f32_e32 v14, v14
	v_rcp_f32_e32 v15, v15
	v_pk_fma_f32 v[16:17], v[16:17], v[214:215], v[214:215] op_sel:[0,1,1] op_sel_hi:[1,1,1]
	v_rcp_f32_e32 v8, v16
	v_rcp_f32_e32 v9, v17
	v_pk_mul_f32 v[6:7], v[2:3], v[14:15]
	v_pk_mul_f32 v[8:9], v[4:5], v[8:9]
	v_cvt_pk_bf16_f32 v2, v10, v11
	v_cvt_pk_bf16_f32 v3, v12, v13
	v_cvt_pk_bf16_f32 v4, v6, v7
	v_cvt_pk_bf16_f32 v5, v8, v9
	s_add_u32 s28, s4, 0xf2000
	s_addc_u32 s29, s5, 0
	global_store_dwordx4 v207, v[2:5], s[28:29]
	s_cbranch_vccnz .LBB0_166
	s_andn2_b64 vcc, exec, s[0:1]
	s_cbranch_vccnz .LBB0_165
	s_barrier
	s_branch .LBB0_165

.LBB0_1923:
	v_mov_b32_e32 v254, 1.0
	v_lshl_add_u32 v202, s56, 8, v1
	s_and_b32 s72, s71, 1
	s_lshl_b32 s72, s72, 12
	s_add_i32 s72, s72, 0x20000
	v_lshl_add_u32 v206, v1, 4, s72
	v_add_u32_e32 v156, 0x80, v202
	ds_read_b128 v[170:173], v206
	ds_read_b128 v[174:177], v206 offset:256
	ds_read_b128 v[178:181], v206 offset:512
	ds_read_b128 v[182:185], v206 offset:768
	ds_read_b128 v[186:189], v206 offset:2048
	ds_read_b128 v[190:193], v206 offset:2304
	ds_read_b128 v[194:197], v206 offset:2560
	ds_read_b128 v[198:201], v206 offset:2816
	v_pk_mul_f32 v[124:125], v[128:129], v[124:125]
	v_pk_mul_f32 v[122:123], v[126:127], v[122:123]
	v_pk_mul_f32 v[116:117], v[120:121], v[116:117]
	v_lshl_or_b32 v204, s14, 7, v164
	v_pk_mul_f32 v[114:115], v[118:119], v[114:115]
	v_mul_u32_u24_e32 v207, s70, v202
	v_lshl_add_u32 v207, v204, 1, v207
	v_pk_mul_f32 v[108:109], v[112:113], v[108:109]
	v_pk_mul_f32 v[106:107], v[110:111], v[106:107]
	v_pk_mul_f32 v[100:101], v[104:105], v[100:101]
	v_pk_mul_f32 v[98:99], v[102:103], v[98:99]
	v_pk_mul_f32 v[92:93], v[96:97], v[92:93]
	v_pk_mul_f32 v[90:91], v[94:95], v[90:91]
	v_pk_mul_f32 v[84:85], v[88:89], v[84:85]
	v_pk_mul_f32 v[82:83], v[86:87], v[82:83]
	v_pk_mul_f32 v[76:77], v[80:81], v[76:77]
	v_pk_mul_f32 v[74:75], v[78:79], v[74:75]
	v_pk_mul_f32 v[68:69], v[72:73], v[68:69]
	v_pk_mul_f32 v[66:67], v[70:71], v[66:67]
	v_pk_mul_f32 v[60:61], v[64:65], v[60:61]
	v_pk_mul_f32 v[58:59], v[62:63], v[58:59]
	v_pk_mul_f32 v[52:53], v[56:57], v[52:53]
	v_pk_mul_f32 v[50:51], v[54:55], v[50:51]
	v_pk_mul_f32 v[44:45], v[48:49], v[44:45]
	v_pk_mul_f32 v[42:43], v[46:47], v[42:43]
	v_pk_mul_f32 v[36:37], v[40:41], v[36:37]
	v_pk_mul_f32 v[34:35], v[38:39], v[34:35]
	v_pk_mul_f32 v[28:29], v[32:33], v[28:29]
	v_pk_mul_f32 v[26:27], v[30:31], v[26:27]
	v_pk_mul_f32 v[20:21], v[24:25], v[20:21]
	v_pk_mul_f32 v[18:19], v[22:23], v[18:19]
	v_pk_mul_f32 v[12:13], v[16:17], v[12:13]
	v_pk_mul_f32 v[10:11], v[14:15], v[10:11]
	v_pk_mul_f32 v[4:5], v[8:9], v[4:5]
	v_pk_mul_f32 v[2:3], v[6:7], v[2:3]
	s_andn2_b64 vcc, exec, s[46:47]
	s_waitcnt lgkmcnt(0)
	v_add_f32_e32 v152, v170, v171
	v_add_f32_e32 v153, v172, v173
	v_add_f32_e32 v149, v152, v153
	v_fmamk_f32 v208, v149, 0x3a800000, v168
	v_add_f32_e32 v174, v174, v175
	v_add_f32_e32 v176, v176, v177
	v_rsq_f32_e32 v163, v208
	v_add_f32_e32 v151, v174, v176
	v_add_f32_e32 v178, v178, v179
	v_add_f32_e32 v180, v180, v181
	v_add_f32_e32 v152, v178, v180
	v_add_f32_e32 v182, v182, v183
	v_add_f32_e32 v184, v184, v185
	v_add_f32_e32 v153, v182, v184
	v_add_f32_e32 v186, v186, v187
	v_add_f32_e32 v188, v188, v189
	v_add_f32_e32 v155, v186, v188
	v_add_f32_e32 v190, v190, v191
	v_add_f32_e32 v192, v192, v193
	v_add_f32_e32 v157, v190, v192
	v_add_f32_e32 v194, v194, v195
	v_add_f32_e32 v196, v196, v197
	v_add_f32_e32 v159, v194, v196
	v_add_f32_e32 v198, v198, v199
	v_add_f32_e32 v200, v200, v201
	v_add_f32_e32 v161, v198, v200
	v_fmamk_f32 v209, v151, 0x3a800000, v168
	v_fmamk_f32 v210, v152, 0x3a800000, v168
	v_fmamk_f32 v211, v153, 0x3a800000, v168
	v_fmamk_f32 v212, v155, 0x3a800000, v168
	v_fmamk_f32 v213, v157, 0x3a800000, v168
	v_fmamk_f32 v214, v159, 0x3a800000, v168
	v_fmamk_f32 v215, v161, 0x3a800000, v168
	v_rsq_f32_e32 v169, v210
	v_rsq_f32_e32 v151, v214
	v_mul_f32_e32 v157, 0xbfb8aa3b, v163
	v_rsq_f32_e32 v161, v209
	v_rsq_f32_e32 v149, v215
	v_pk_mul_f32 v[174:175], v[126:127], v[156:157] op_sel:[0,1] op_sel_hi:[1,1]
	v_exp_f32_e32 v174, v174
	v_exp_f32_e32 v175, v175
	s_nop 0
	v_pk_fma_f32 v[174:175], v[174:175], v[208:209], v[208:209] op_sel:[0,0,0] op_sel_hi:[1,0,0]
	v_rcp_f32_e32 v174, v174
	v_rcp_f32_e32 v175, v175
	v_pk_mul_f32 v[128:129], v[128:129], v[156:157] op_sel:[0,1] op_sel_hi:[1,1]
	v_exp_f32_e32 v128, v128
	v_exp_f32_e32 v129, v129
	v_rsq_f32_e32 v173, v211
	v_rsq_f32_e32 v176, v212
	v_pk_fma_f32 v[128:129], v[128:129], v[208:209], v[208:209] op_sel:[0,0,0] op_sel_hi:[1,0,0]
	v_rcp_f32_e32 v128, v128
	v_rcp_f32_e32 v129, v129
	v_pk_mul_f32 v[122:123], v[122:123], v[174:175]
	v_pk_mul_f32 v[124:125], v[124:125], v[128:129]
	v_pk_mul_f32 v[128:129], v[118:119], v[156:157] op_sel:[0,1] op_sel_hi:[1,1]
	v_exp_f32_e32 v128, v128
	v_exp_f32_e32 v129, v129
	s_nop 0
	v_pk_fma_f32 v[126:127], v[128:129], v[208:209], v[208:209] op_sel:[0,0,0] op_sel_hi:[1,0,0]
	v_mul_f32_e32 v128, v120, v157
	v_mul_f32_e32 v129, v121, v157
	v_exp_f32_e32 v128, v128
	v_exp_f32_e32 v129, v129
	v_rcp_f32_e32 v126, v126
	v_rcp_f32_e32 v127, v127
	v_fma_f32 v120, v128, v208, v208
	v_fma_f32 v121, v129, v208, v208
	v_rcp_f32_e32 v120, v120
	v_rcp_f32_e32 v121, v121
	v_pk_mul_f32 v[118:119], v[114:115], v[126:127]
	v_rsq_f32_e32 v155, v213
	v_pk_mul_f32 v[120:121], v[116:117], v[120:121]
	v_cvt_pk_bf16_f32 v116, v122, v123
	v_cvt_pk_bf16_f32 v117, v124, v125
	v_cvt_pk_bf16_f32 v118, v118, v119
	v_cvt_pk_bf16_f32 v119, v120, v121
	global_store_dwordx4 v207, v[116:119], s[18:19]
	s_nop 1
	v_mul_f32_e32 v119, 0xbfb8aa3b, v161
	v_pk_mul_f32 v[120:121], v[110:111], v[118:119] op_sel:[0,1] op_sel_hi:[1,1]
	v_exp_f32_e32 v120, v120
	v_exp_f32_e32 v121, v121
	v_pk_mul_f32 v[122:123], v[112:113], v[118:119] op_sel:[0,1] op_sel_hi:[1,1]
	v_exp_f32_e32 v122, v122
	v_exp_f32_e32 v123, v123
	v_pk_fma_f32 v[120:121], v[120:121], v[208:209], v[208:209] op_sel:[0,1,1] op_sel_hi:[1,1,1]
	v_rcp_f32_e32 v120, v120
	v_rcp_f32_e32 v121, v121
	v_pk_fma_f32 v[122:123], v[122:123], v[208:209], v[208:209] op_sel:[0,1,1] op_sel_hi:[1,1,1]
	v_rcp_f32_e32 v112, v122
	v_rcp_f32_e32 v113, v123
	v_pk_mul_f32 v[106:107], v[106:107], v[120:121]
	v_pk_mul_f32 v[108:109], v[108:109], v[112:113]
	v_pk_mul_f32 v[112:113], v[102:103], v[118:119] op_sel:[0,1] op_sel_hi:[1,1]
	v_exp_f32_e32 v112, v112
	v_exp_f32_e32 v113, v113
	s_nop 0
	v_pk_fma_f32 v[110:111], v[112:113], v[208:209], v[208:209] op_sel:[0,1,1] op_sel_hi:[1,1,1]
	v_pk_mul_f32 v[112:113], v[104:105], v[118:119] op_sel:[0,1] op_sel_hi:[1,1]
	v_exp_f32_e32 v112, v112
	v_exp_f32_e32 v113, v113
	v_rcp_f32_e32 v110, v110
	v_rcp_f32_e32 v111, v111
	v_pk_fma_f32 v[112:113], v[112:113], v[208:209], v[208:209] op_sel:[0,1,1] op_sel_hi:[1,1,1]
	v_rcp_f32_e32 v104, v112
	v_rcp_f32_e32 v105, v113
	v_pk_mul_f32 v[102:103], v[98:99], v[110:111]
	v_pk_mul_f32 v[104:105], v[100:101], v[104:105]
	v_cvt_pk_bf16_f32 v98, v106, v107
	v_cvt_pk_bf16_f32 v99, v108, v109
	v_cvt_pk_bf16_f32 v100, v102, v103
	v_cvt_pk_bf16_f32 v101, v104, v105
	s_add_u32 s28, s18, 0x16000
	s_addc_u32 s29, s19, 0
	global_store_dwordx4 v207, v[98:101], s[28:29]
	s_nop 1
	v_mul_f32_e32 v101, 0xbfb8aa3b, v169
	v_pk_mul_f32 v[102:103], v[94:95], v[100:101] op_sel:[0,1] op_sel_hi:[1,1]
	v_exp_f32_e32 v102, v102
	v_exp_f32_e32 v103, v103
	v_pk_mul_f32 v[104:105], v[96:97], v[100:101] op_sel:[0,1] op_sel_hi:[1,1]
	v_exp_f32_e32 v104, v104
	v_exp_f32_e32 v105, v105
	v_pk_fma_f32 v[102:103], v[102:103], v[210:211], v[210:211] op_sel:[0,0,0] op_sel_hi:[1,0,0]
	v_rcp_f32_e32 v102, v102
	v_rcp_f32_e32 v103, v103
	v_pk_fma_f32 v[104:105], v[104:105], v[210:211], v[210:211] op_sel:[0,0,0] op_sel_hi:[1,0,0]
	v_rcp_f32_e32 v96, v104
	v_rcp_f32_e32 v97, v105
	v_pk_mul_f32 v[90:91], v[90:91], v[102:103]
	v_pk_mul_f32 v[92:93], v[92:93], v[96:97]
	v_pk_mul_f32 v[96:97], v[86:87], v[100:101] op_sel:[0,1] op_sel_hi:[1,1]
	v_exp_f32_e32 v96, v96
	v_exp_f32_e32 v97, v97
	s_nop 0
	v_pk_fma_f32 v[94:95], v[96:97], v[210:211], v[210:211] op_sel:[0,0,0] op_sel_hi:[1,0,0]
	v_pk_mul_f32 v[96:97], v[88:89], v[100:101] op_sel:[0,1] op_sel_hi:[1,1]
	v_exp_f32_e32 v96, v96
	v_exp_f32_e32 v97, v97
	v_rcp_f32_e32 v94, v94
	v_rcp_f32_e32 v95, v95
	v_pk_fma_f32 v[96:97], v[96:97], v[210:211], v[210:211] op_sel:[0,0,0] op_sel_hi:[1,0,0]
	v_rcp_f32_e32 v88, v96
	v_rcp_f32_e32 v89, v97
	v_pk_mul_f32 v[86:87], v[82:83], v[94:95]
	v_pk_mul_f32 v[88:89], v[84:85], v[88:89]
	v_cvt_pk_bf16_f32 v82, v90, v91
	v_cvt_pk_bf16_f32 v83, v92, v93
	v_cvt_pk_bf16_f32 v84, v86, v87
	v_cvt_pk_bf16_f32 v85, v88, v89
	s_add_u32 s28, s18, 0x2c000
	s_addc_u32 s29, s19, 0
	global_store_dwordx4 v207, v[82:85], s[28:29]
	s_nop 1
	v_mul_f32_e32 v85, 0xbfb8aa3b, v173
	v_pk_mul_f32 v[86:87], v[78:79], v[84:85] op_sel:[0,1] op_sel_hi:[1,1]
	v_exp_f32_e32 v86, v86
	v_exp_f32_e32 v87, v87
	v_pk_mul_f32 v[88:89], v[80:81], v[84:85] op_sel:[0,1] op_sel_hi:[1,1]
	v_exp_f32_e32 v88, v88
	v_exp_f32_e32 v89, v89
	v_pk_fma_f32 v[86:87], v[86:87], v[210:211], v[210:211] op_sel:[0,1,1] op_sel_hi:[1,1,1]
	v_rcp_f32_e32 v86, v86
	v_rcp_f32_e32 v87, v87
	v_pk_fma_f32 v[88:89], v[88:89], v[210:211], v[210:211] op_sel:[0,1,1] op_sel_hi:[1,1,1]
	v_rcp_f32_e32 v80, v88
	v_rcp_f32_e32 v81, v89
	v_pk_mul_f32 v[74:75], v[74:75], v[86:87]
	v_pk_mul_f32 v[76:77], v[76:77], v[80:81]
	v_pk_mul_f32 v[80:81], v[70:71], v[84:85] op_sel:[0,1] op_sel_hi:[1,1]
	v_exp_f32_e32 v80, v80
	v_exp_f32_e32 v81, v81
	s_nop 0
	v_pk_fma_f32 v[78:79], v[80:81], v[210:211], v[210:211] op_sel:[0,1,1] op_sel_hi:[1,1,1]
	v_pk_mul_f32 v[80:81], v[72:73], v[84:85] op_sel:[0,1] op_sel_hi:[1,1]
	v_exp_f32_e32 v80, v80
	v_exp_f32_e32 v81, v81
	v_rcp_f32_e32 v78, v78
	v_rcp_f32_e32 v79, v79
	v_pk_fma_f32 v[80:81], v[80:81], v[210:211], v[210:211] op_sel:[0,1,1] op_sel_hi:[1,1,1]
	v_rcp_f32_e32 v72, v80
	v_rcp_f32_e32 v73, v81
	v_pk_mul_f32 v[70:71], v[66:67], v[78:79]
	v_pk_mul_f32 v[72:73], v[68:69], v[72:73]
	v_cvt_pk_bf16_f32 v66, v74, v75
	v_cvt_pk_bf16_f32 v67, v76, v77
	v_cvt_pk_bf16_f32 v68, v70, v71
	v_cvt_pk_bf16_f32 v69, v72, v73
	s_add_u32 s28, s18, 0x42000
	s_addc_u32 s29, s19, 0
	global_store_dwordx4 v207, v[66:69], s[28:29]
	s_nop 1
	v_mul_f32_e32 v69, 0xbfb8aa3b, v176
	v_pk_mul_f32 v[70:71], v[62:63], v[68:69] op_sel:[0,1] op_sel_hi:[1,1]
	v_exp_f32_e32 v70, v70
	v_exp_f32_e32 v71, v71
	v_pk_mul_f32 v[72:73], v[64:65], v[68:69] op_sel:[0,1] op_sel_hi:[1,1]
	v_exp_f32_e32 v72, v72
	v_exp_f32_e32 v73, v73
	v_pk_fma_f32 v[70:71], v[70:71], v[212:213], v[212:213] op_sel:[0,0,0] op_sel_hi:[1,0,0]
	v_rcp_f32_e32 v70, v70
	v_rcp_f32_e32 v71, v71
	v_pk_fma_f32 v[72:73], v[72:73], v[212:213], v[212:213] op_sel:[0,0,0] op_sel_hi:[1,0,0]
	v_rcp_f32_e32 v64, v72
	v_rcp_f32_e32 v65, v73
	v_pk_mul_f32 v[58:59], v[58:59], v[70:71]
	v_pk_mul_f32 v[60:61], v[60:61], v[64:65]
	v_pk_mul_f32 v[64:65], v[54:55], v[68:69] op_sel:[0,1] op_sel_hi:[1,1]
	v_exp_f32_e32 v64, v64
	v_exp_f32_e32 v65, v65
	s_nop 0
	v_pk_fma_f32 v[62:63], v[64:65], v[212:213], v[212:213] op_sel:[0,0,0] op_sel_hi:[1,0,0]
	v_pk_mul_f32 v[64:65], v[56:57], v[68:69] op_sel:[0,1] op_sel_hi:[1,1]
	v_exp_f32_e32 v64, v64
	v_exp_f32_e32 v65, v65
	v_rcp_f32_e32 v62, v62
	v_rcp_f32_e32 v63, v63
	v_pk_fma_f32 v[64:65], v[64:65], v[212:213], v[212:213] op_sel:[0,0,0] op_sel_hi:[1,0,0]
	v_rcp_f32_e32 v56, v64
	v_rcp_f32_e32 v57, v65
	v_pk_mul_f32 v[54:55], v[50:51], v[62:63]
	v_pk_mul_f32 v[56:57], v[52:53], v[56:57]
	v_cvt_pk_bf16_f32 v50, v58, v59
	v_cvt_pk_bf16_f32 v51, v60, v61
	v_cvt_pk_bf16_f32 v52, v54, v55
	v_cvt_pk_bf16_f32 v53, v56, v57
	s_add_u32 s28, s18, 0xb0000
	s_addc_u32 s29, s19, 0
	global_store_dwordx4 v207, v[50:53], s[28:29]
	s_nop 1
	v_mul_f32_e32 v53, 0xbfb8aa3b, v155
	v_pk_mul_f32 v[54:55], v[46:47], v[52:53] op_sel:[0,1] op_sel_hi:[1,1]
	v_exp_f32_e32 v54, v54
	v_exp_f32_e32 v55, v55
	v_pk_mul_f32 v[56:57], v[48:49], v[52:53] op_sel:[0,1] op_sel_hi:[1,1]
	v_exp_f32_e32 v56, v56
	v_exp_f32_e32 v57, v57
	v_pk_fma_f32 v[54:55], v[54:55], v[212:213], v[212:213] op_sel:[0,1,1] op_sel_hi:[1,1,1]
	v_rcp_f32_e32 v54, v54
	v_rcp_f32_e32 v55, v55
	v_pk_fma_f32 v[56:57], v[56:57], v[212:213], v[212:213] op_sel:[0,1,1] op_sel_hi:[1,1,1]
	v_rcp_f32_e32 v48, v56
	v_rcp_f32_e32 v49, v57
	v_pk_mul_f32 v[42:43], v[42:43], v[54:55]
	v_pk_mul_f32 v[44:45], v[44:45], v[48:49]
	v_pk_mul_f32 v[48:49], v[38:39], v[52:53] op_sel:[0,1] op_sel_hi:[1,1]
	v_exp_f32_e32 v48, v48
	v_exp_f32_e32 v49, v49
	s_nop 0
	v_pk_fma_f32 v[46:47], v[48:49], v[212:213], v[212:213] op_sel:[0,1,1] op_sel_hi:[1,1,1]
	v_pk_mul_f32 v[48:49], v[40:41], v[52:53] op_sel:[0,1] op_sel_hi:[1,1]
	v_exp_f32_e32 v48, v48
	v_exp_f32_e32 v49, v49
	v_rcp_f32_e32 v46, v46
	v_rcp_f32_e32 v47, v47
	v_pk_fma_f32 v[48:49], v[48:49], v[212:213], v[212:213] op_sel:[0,1,1] op_sel_hi:[1,1,1]
	v_rcp_f32_e32 v40, v48
	v_rcp_f32_e32 v41, v49
	v_pk_mul_f32 v[38:39], v[34:35], v[46:47]
	v_pk_mul_f32 v[40:41], v[36:37], v[40:41]
	v_cvt_pk_bf16_f32 v34, v42, v43
	v_cvt_pk_bf16_f32 v35, v44, v45
	v_cvt_pk_bf16_f32 v36, v38, v39
	v_cvt_pk_bf16_f32 v37, v40, v41
	s_add_u32 s28, s18, 0xc6000
	s_addc_u32 s29, s19, 0
	global_store_dwordx4 v207, v[34:37], s[28:29]
	s_nop 1
	v_mul_f32_e32 v37, 0xbfb8aa3b, v151
	v_pk_mul_f32 v[38:39], v[30:31], v[36:37] op_sel:[0,1] op_sel_hi:[1,1]
	v_exp_f32_e32 v38, v38
	v_exp_f32_e32 v39, v39
	v_pk_mul_f32 v[40:41], v[32:33], v[36:37] op_sel:[0,1] op_sel_hi:[1,1]
	v_exp_f32_e32 v40, v40
	v_exp_f32_e32 v41, v41
	v_pk_fma_f32 v[38:39], v[38:39], v[214:215], v[214:215] op_sel:[0,0,0] op_sel_hi:[1,0,0]
	v_rcp_f32_e32 v38, v38
	v_rcp_f32_e32 v39, v39
	v_pk_fma_f32 v[40:41], v[40:41], v[214:215], v[214:215] op_sel:[0,0,0] op_sel_hi:[1,0,0]
	v_rcp_f32_e32 v32, v40
	v_rcp_f32_e32 v33, v41
	v_pk_mul_f32 v[26:27], v[26:27], v[38:39]
	v_pk_mul_f32 v[28:29], v[28:29], v[32:33]
	v_pk_mul_f32 v[32:33], v[22:23], v[36:37] op_sel:[0,1] op_sel_hi:[1,1]
	v_exp_f32_e32 v32, v32
	v_exp_f32_e32 v33, v33
	s_nop 0
	v_pk_fma_f32 v[30:31], v[32:33], v[214:215], v[214:215] op_sel:[0,0,0] op_sel_hi:[1,0,0]
	v_pk_mul_f32 v[32:33], v[24:25], v[36:37] op_sel:[0,1] op_sel_hi:[1,1]
	v_exp_f32_e32 v32, v32
	v_exp_f32_e32 v33, v33
	v_rcp_f32_e32 v30, v30
	v_rcp_f32_e32 v31, v31
	v_pk_fma_f32 v[32:33], v[32:33], v[214:215], v[214:215] op_sel:[0,0,0] op_sel_hi:[1,0,0]
	v_rcp_f32_e32 v24, v32
	v_rcp_f32_e32 v25, v33
	v_pk_mul_f32 v[22:23], v[18:19], v[30:31]
	v_pk_mul_f32 v[24:25], v[20:21], v[24:25]
	v_cvt_pk_bf16_f32 v18, v26, v27
	v_cvt_pk_bf16_f32 v19, v28, v29
	v_cvt_pk_bf16_f32 v20, v22, v23
	v_cvt_pk_bf16_f32 v21, v24, v25
	s_add_u32 s28, s18, 0xdc000
	s_addc_u32 s29, s19, 0
	global_store_dwordx4 v207, v[18:21], s[28:29]
	s_nop 1
	v_mul_f32_e32 v21, 0xbfb8aa3b, v149
	v_pk_mul_f32 v[22:23], v[14:15], v[20:21] op_sel:[0,1] op_sel_hi:[1,1]
	v_exp_f32_e32 v22, v22
	v_exp_f32_e32 v23, v23
	v_pk_mul_f32 v[24:25], v[16:17], v[20:21] op_sel:[0,1] op_sel_hi:[1,1]
	v_exp_f32_e32 v24, v24
	v_exp_f32_e32 v25, v25
	v_pk_fma_f32 v[22:23], v[22:23], v[214:215], v[214:215] op_sel:[0,1,1] op_sel_hi:[1,1,1]
	v_rcp_f32_e32 v22, v22
	v_rcp_f32_e32 v23, v23
	v_pk_fma_f32 v[24:25], v[24:25], v[214:215], v[214:215] op_sel:[0,1,1] op_sel_hi:[1,1,1]
	v_rcp_f32_e32 v16, v24
	v_rcp_f32_e32 v17, v25
	v_pk_mul_f32 v[10:11], v[10:11], v[22:23]
	v_pk_mul_f32 v[12:13], v[12:13], v[16:17]
	v_pk_mul_f32 v[16:17], v[6:7], v[20:21] op_sel:[0,1] op_sel_hi:[1,1]
	v_exp_f32_e32 v16, v16
	v_exp_f32_e32 v17, v17
	s_nop 0
	v_pk_fma_f32 v[14:15], v[16:17], v[214:215], v[214:215] op_sel:[0,1,1] op_sel_hi:[1,1,1]
	v_pk_mul_f32 v[16:17], v[8:9], v[20:21] op_sel:[0,1] op_sel_hi:[1,1]
	v_exp_f32_e32 v16, v16
	v_exp_f32_e32 v17, v17
	v_rcp_f32_e32 v14, v14
	v_rcp_f32_e32 v15, v15
	v_pk_fma_f32 v[16:17], v[16:17], v[214:215], v[214:215] op_sel:[0,1,1] op_sel_hi:[1,1,1]
	v_rcp_f32_e32 v8, v16
	v_rcp_f32_e32 v9, v17
	v_pk_mul_f32 v[6:7], v[2:3], v[14:15]
	v_pk_mul_f32 v[8:9], v[4:5], v[8:9]
	v_cvt_pk_bf16_f32 v2, v10, v11
	v_cvt_pk_bf16_f32 v3, v12, v13
	v_cvt_pk_bf16_f32 v4, v6, v7
	v_cvt_pk_bf16_f32 v5, v8, v9
	s_add_u32 s28, s18, 0xf2000
	s_addc_u32 s29, s19, 0
	global_store_dwordx4 v207, v[2:5], s[28:29]
	s_cbranch_vccnz .LBB0_1929
	s_ashr_i32 s14, s14, 2
	s_cmp_lt_i32 s14, 4
	s_cbranch_scc1 .LBB0_1929
	s_waitcnt vmcnt(0)
	s_and_saveexec_b64 s[28:29], s[2:3]
	s_cbranch_execz .LBB0_1928
	s_mov_b64 s[30:31], exec
	v_mbcnt_lo_u32_b32 v2, s30, 0
	v_mbcnt_hi_u32_b32 v2, s31, v2
	v_cmp_eq_u32_e32 vcc, 0, v2
	s_and_b64 s[58:59], exec, vcc
	s_mov_b64 exec, s[58:59]
	s_cbranch_execz .LBB0_1928
	s_lshl_b32 s14, s14, 6
	s_addk_i32 s14, 0xff00
	s_lshl_b64 s[58:59], s[14:15], 2
	s_add_u32 s58, s38, s58
	s_addc_u32 s59, s39, s59
	s_bcnt1_i32_b64 s14, s[30:31]
	v_mov_b32_e32 v2, s14
	global_atomic_add v133, v2, s[58:59]
